# no grid barrier between the first half's down GEMM and the second half's up GEMM (no cross-workgroup dependence); skinny GEMM K loops (gates/merge/out/up/down): loads issued in batches with counted wa
# speedup vs baseline: 1.0038x; 1.0038x over previous
; __device__ __forceinline__ float sigm(float x) { return __builtin_amdgcn_rcpf(1.0f + __expf(-x)); }
; __device__ __forceinline__ unsigned pk2(float lo, float hi) { f32x2_t v = {lo, hi}; bf16x2_t b = __builtin_convertvector(v, bf16x2_t); return __builtin_bit_cast(unsigned, b); }
; __device__ __forceinline__ float sigm(float x) { return __builtin_amdgcn_rcpf(1.0f + __expf(-x)); }
; template <int MODE, int NSEL> __device__ __forceinline__ void skinny_phase(const bf16_t* A, int lda, size_t asel, const bf16_t* Bt, size_t bsel, int K, int N, unsigned char* lds, int tid, int bx, int G, ...
;     ...
;     for (int blk = G - 1 - bx; blk < (N >> 5); blk += G) {
; #pragma unroll
;         for (int s = 0; s < NSEL; ++s) {
;             const bf16_t* ap = A + s * asel + (size_t)(lane & 31) * lda + w * kw + 8 * (lane >> 5);
;             const bf16_t* bp = Bt + s * bsel + (size_t)(blk * 32 + (lane & 31)) * K + w * kw + 8 * (lane >> 5);
;             f32x16 acc;
; #pragma unroll
;             for (int i = 0; i < 16; ++i) acc[i] = 0.f;
; #pragma unroll 8
;             for (int k = 0; k < kw; k += 16) { const bf16x8 bv = *(const bf16x8*)(bp + k); const bf16x8 av = *(const bf16x8*)(ap + k); acc = __builtin_amdgcn_mfma_f32_32x32x16_bf16(bv, av, acc, 0, 0, 0); }
; #pragma unroll
;             for (int i = 0; i < 16; ++i) red[((s * 8 + w) * 16 + i) * 64 + lane] = acc[i];
;         }
;         __syncthreads();
;         const int row = lane & 31, col = blk * 32 + 8 * (w >> 1) + 4 * (lane >> 5) + 2 * (w & 1);
;         float v[NSEL][2];
; #pragma unroll
;         for (int s = 0; s < NSEL; ++s)
; #pragma unroll
;             for (int e = 0; e < 2; ++e) { float t = 0.f;
; #pragma unroll
;                 for (int ww = 0; ww < 8; ++ww) t += red[((s * 8 + ww) * 16 + 2 * w + e) * 64 + lane]; v[s][e] = t; }
;         if (MODE == 1) { *(unsigned*)(Ob + (size_t)row * ldo + col) = pk2(sigm(v[0][0]), sigm(v[0][1])); }
.LBB0_1158:
	global_load_dwordx4 v[76:79], v[26:27], off offset:-128
	global_load_dwordx4 v[80:83], v[28:29], off offset:-128
	global_load_dwordx4 v[84:87], v[26:27], off offset:-96
	global_load_dwordx4 v[90:93], v[28:29], off offset:-96
	global_load_dwordx4 v[94:97], v[26:27], off offset:-64
	global_load_dwordx4 v[98:101], v[28:29], off offset:-64
	global_load_dwordx4 v[102:105], v[26:27], off offset:-32
	global_load_dwordx4 v[112:115], v[28:29], off offset:-32
	global_load_dwordx4 v[116:119], v[26:27], off
	global_load_dwordx4 v[120:123], v[28:29], off
	global_load_dwordx4 v[128:131], v[26:27], off offset:32
	global_load_dwordx4 v[132:135], v[28:29], off offset:32
	global_load_dwordx4 v[136:139], v[26:27], off offset:64
	global_load_dwordx4 v[140:143], v[28:29], off offset:64
	s_nop 0
	s_addk_i32 s4, 0x80
	s_cmpk_gt_u32 s4, 0xef
	s_waitcnt vmcnt(12)
	v_mfma_f32_32x32x16_bf16 v[0:15], v[76:79], v[80:83], v[0:15]
	s_nop 0
	s_nop 0
	s_waitcnt vmcnt(10)
	v_mfma_f32_32x32x16_bf16 v[0:15], v[84:87], v[90:93], v[0:15]
	s_nop 0
	s_nop 0
	s_waitcnt vmcnt(8)
	v_mfma_f32_32x32x16_bf16 v[0:15], v[94:97], v[98:101], v[0:15]
	s_nop 0
	s_nop 0
	s_waitcnt vmcnt(6)
	v_mfma_f32_32x32x16_bf16 v[0:15], v[102:105], v[112:115], v[0:15]
	s_nop 0
	s_nop 0
	s_waitcnt vmcnt(4)
	v_mfma_f32_32x32x16_bf16 v[0:15], v[116:119], v[120:123], v[0:15]
	s_nop 0
	s_nop 0
	s_waitcnt vmcnt(2)
	v_mfma_f32_32x32x16_bf16 v[0:15], v[128:131], v[132:135], v[0:15]
	s_nop 0
	s_nop 0
	s_waitcnt vmcnt(0)
	v_mfma_f32_32x32x16_bf16 v[0:15], v[136:139], v[140:143], v[0:15]
	global_load_dwordx4 v[32:35], v[26:27], off offset:96
	global_load_dwordx4 v[36:39], v[28:29], off offset:96
	v_lshl_add_u64 v[28:29], v[28:29], 0, s[64:65]
	v_lshl_add_u64 v[26:27], v[26:27], 0, s[64:65]
	s_waitcnt vmcnt(0)
	v_mfma_f32_32x32x16_bf16 v[0:15], v[32:35], v[36:39], v[0:15]
	s_cbranch_scc0 .LBB0_1158
	s_nop 10
	ds_write2st64_b32 v30, v0, v1 offset1:1
	ds_write2st64_b32 v30, v2, v3 offset0:2 offset1:3
	ds_write2st64_b32 v30, v4, v5 offset0:4 offset1:5
	ds_write2st64_b32 v30, v6, v7 offset0:6 offset1:7
	ds_write2st64_b32 v30, v8, v9 offset0:8 offset1:9
	ds_write2st64_b32 v30, v10, v11 offset0:10 offset1:11
	ds_write2st64_b32 v30, v12, v13 offset0:12 offset1:13
	ds_write2st64_b32 v30, v14, v15 offset0:14 offset1:15
	s_waitcnt lgkmcnt(0)
	s_barrier
	ds_read2st64_b32 v[0:1], v31 offset1:1
	ds_read2st64_b32 v[2:3], v31 offset0:16 offset1:17
	ds_read2st64_b32 v[4:5], v31 offset0:32 offset1:33
	ds_read2st64_b32 v[6:7], v31 offset0:48 offset1:49
	ds_read2st64_b32 v[8:9], v31 offset0:64 offset1:65
	ds_read2st64_b32 v[10:11], v31 offset0:80 offset1:81
	ds_read2st64_b32 v[12:13], v31 offset0:96 offset1:97
	ds_read2st64_b32 v[14:15], v31 offset0:112 offset1:113
	s_waitcnt lgkmcnt(7)
	v_add_f32_e32 v0, 0, v0
	s_waitcnt lgkmcnt(6)
	v_add_f32_e32 v0, v0, v2
	v_add_f32_e32 v1, 0, v1
	s_waitcnt lgkmcnt(5)
	v_add_f32_e32 v0, v0, v4
	v_add_f32_e32 v1, v1, v3
	s_waitcnt lgkmcnt(4)
	v_add_f32_e32 v0, v0, v6
	v_add_f32_e32 v1, v1, v5
	s_waitcnt lgkmcnt(3)
	v_add_f32_e32 v0, v0, v8
	v_add_f32_e32 v1, v1, v7
	s_waitcnt lgkmcnt(2)
	v_add_f32_e32 v0, v0, v10
	v_add_f32_e32 v1, v1, v9
	s_waitcnt lgkmcnt(1)
	v_add_f32_e32 v0, v0, v12
	v_add_f32_e32 v1, v1, v11
	s_waitcnt lgkmcnt(0)
	v_add_f32_e32 v0, v0, v14
	v_add_f32_e32 v1, v1, v13
	v_add_f32_e32 v1, v1, v15
	v_mul_f32_e32 v0, 0xbfb8aa3b, v0
	v_exp_f32_e32 v0, v0
	v_mul_f32_e32 v1, 0xbfb8aa3b, v1
	v_exp_f32_e32 v1, v1
	s_add_i32 s4, s3, 0x100
	v_add_f32_e32 v0, 1.0, v0
	v_rcp_f32_e32 v2, v0
	v_add_f32_e32 v0, 1.0, v1
	v_rcp_f32_e32 v1, v0
	v_lshl_add_u32 v0, s3, 5, v17
	v_add_u32_e32 v24, 0x2000, v24
	s_cmpk_gt_i32 s3, 0xffbf
	v_cvt_pk_bf16_f32 v2, v2, v1
	v_ashrrev_i32_e32 v1, 31, v0
	v_lshl_add_u64 v[0:1], v[0:1], 1, v[18:19]
	s_mov_b32 s3, s4
	global_store_dword v[0:1], v2, off
	s_barrier
	s_cbranch_scc0 .LBB0_1157

; template <int MODE, int NSEL> __device__ __forceinline__ void skinny_phase(const bf16_t* A, int lda, size_t asel, const bf16_t* Bt, size_t bsel, int K, int N, unsigned char* lds, int tid, int bx, int G, ...
;     ...
;         for (int s = 0; s < NSEL; ++s) {
;             const bf16_t* ap = A + s * asel + (size_t)(lane & 31) * lda + w * kw + 8 * (lane >> 5);
;             const bf16_t* bp = Bt + s * bsel + (size_t)(blk * 32 + (lane & 31)) * K + w * kw + 8 * (lane >> 5);
;             f32x16 acc;
; #pragma unroll
;             for (int i = 0; i < 16; ++i) acc[i] = 0.f;
; #pragma unroll 8
;             for (int k = 0; k < kw; k += 16) { const bf16x8 bv = *(const bf16x8*)(bp + k); const bf16x8 av = *(const bf16x8*)(ap + k); acc = __builtin_amdgcn_mfma_f32_32x32x16_bf16(bv, av, acc, 0, 0, 0); }
; #pragma unroll
;             for (int i = 0; i < 16; ++i) red[((s * 8 + w) * 16 + i) * 64 + lane] = acc[i];
.LBB0_1304:
	v_ashrrev_i32_e32 v45, 31, v44
	v_lshlrev_b64 v[0:1], 11, v[44:45]
	v_lshl_add_u64 v[46:47], v[20:21], 0, v[0:1]
	global_load_dwordx4 v[112:115], v[46:47], off
	global_load_dwordx4 v[116:119], v[18:19], off
	global_load_dwordx4 v[120:123], v[46:47], off offset:32
	global_load_dwordx4 v[128:131], v[18:19], off offset:32
	global_load_dwordx4 v[132:135], v[46:47], off offset:64
	global_load_dwordx4 v[136:139], v[18:19], off offset:64
	global_load_dwordx4 v[140:143], v[46:47], off offset:96
	global_load_dwordx4 v[144:147], v[18:19], off offset:96
	global_load_dwordx4 v[148:151], v[46:47], off offset:128
	global_load_dwordx4 v[152:155], v[18:19], off offset:128
	global_load_dwordx4 v[156:159], v[46:47], off offset:160
	global_load_dwordx4 v[160:163], v[18:19], off offset:160
	global_load_dwordx4 v[164:167], v[46:47], off offset:192
	global_load_dwordx4 v[168:171], v[18:19], off offset:192
	global_load_dwordx4 v[172:175], v[46:47], off offset:224
	global_load_dwordx4 v[176:179], v[18:19], off offset:224
	s_nop 0
	s_nop 0
	s_nop 0
	s_mov_b32 s4, 0x400000
	v_add_co_u32_e32 v76, vcc, s4, v46
	v_add_u32_e32 v43, v17, v65
	s_nop 0
	v_addc_co_u32_e32 v77, vcc, 0, v47, vcc
	global_load_dwordx4 v[180:183], v[76:77], off
	global_load_dwordx4 v[184:187], v[18:19], off offset:2048
	global_load_dwordx4 v[188:191], v[76:77], off offset:32
	global_load_dwordx4 v[196:199], v[18:19], off offset:2080
	global_load_dwordx4 v[200:203], v[76:77], off offset:64
	global_load_dwordx4 v[204:207], v[18:19], off offset:2112
	global_load_dwordx4 v[208:211], v[76:77], off offset:96
	global_load_dwordx4 v[216:219], v[18:19], off offset:2144
	global_load_dwordx4 v[220:223], v[76:77], off offset:128
	global_load_dwordx4 v[224:227], v[18:19], off offset:2176
	global_load_dwordx4 v[228:231], v[76:77], off offset:160
	global_load_dwordx4 v[244:247], v[18:19], off offset:2208
	global_load_dwordx4 v[248:251], v[76:77], off offset:192
	s_addk_i32 s3, 0x100
	v_add_u32_e32 v44, 0x2000, v44
	s_cmpk_gt_i32 s3, 0xff3f
	s_waitcnt vmcnt(27)
	v_mfma_f32_32x32x16_bf16 v[0:15], v[112:115], v[116:119], 0
	s_waitcnt vmcnt(25)
	v_mfma_f32_32x32x16_bf16 v[0:15], v[120:123], v[128:131], v[0:15]
	s_nop 0
	s_nop 0
	s_waitcnt vmcnt(23)
	v_mfma_f32_32x32x16_bf16 v[0:15], v[132:135], v[136:139], v[0:15]
	s_nop 0
	s_nop 0
	s_waitcnt vmcnt(21)
	v_mfma_f32_32x32x16_bf16 v[0:15], v[140:143], v[144:147], v[0:15]
	s_nop 0
	s_nop 0
	s_waitcnt vmcnt(19)
	v_mfma_f32_32x32x16_bf16 v[0:15], v[148:151], v[152:155], v[0:15]
	s_nop 0
	s_nop 0
	s_waitcnt vmcnt(17)
	v_mfma_f32_32x32x16_bf16 v[0:15], v[156:159], v[160:163], v[0:15]
	s_nop 0
	s_nop 0
	s_waitcnt vmcnt(15)
	v_mfma_f32_32x32x16_bf16 v[0:15], v[164:167], v[168:171], v[0:15]
	s_nop 0
	s_nop 0
	v_add_co_u32_e32 v46, vcc, s6, v46
	s_nop 1
	v_addc_co_u32_e32 v47, vcc, 0, v47, vcc
	s_waitcnt vmcnt(13)
	v_mfma_f32_32x32x16_bf16 v[0:15], v[172:175], v[176:179], v[0:15]
	s_nop 11
	ds_write2st64_b32 v48, v0, v1 offset1:1
	ds_write2st64_b32 v48, v2, v3 offset0:2 offset1:3
	ds_write2st64_b32 v48, v4, v5 offset0:4 offset1:5
	ds_write2st64_b32 v48, v6, v7 offset0:6 offset1:7
	ds_write2st64_b32 v48, v8, v9 offset0:8 offset1:9
	ds_write2st64_b32 v48, v10, v11 offset0:10 offset1:11
	ds_write2st64_b32 v48, v12, v13 offset0:12 offset1:13
	ds_write2st64_b32 v48, v14, v15 offset0:14 offset1:15
	s_nop 0
	s_nop 0
	s_nop 0
	s_nop 0
	s_waitcnt vmcnt(11)
	v_mfma_f32_32x32x16_bf16 v[0:15], v[180:183], v[184:187], 0
	s_waitcnt vmcnt(9)
	v_mfma_f32_32x32x16_bf16 v[0:15], v[188:191], v[196:199], v[0:15]
	s_nop 0
	s_nop 0
	s_waitcnt vmcnt(7)
	v_mfma_f32_32x32x16_bf16 v[0:15], v[200:203], v[204:207], v[0:15]
	s_nop 0
	s_nop 0
	s_waitcnt vmcnt(5)
	v_mfma_f32_32x32x16_bf16 v[0:15], v[208:211], v[216:219], v[0:15]
	s_nop 0
	s_nop 0
	s_waitcnt vmcnt(3)
	v_mfma_f32_32x32x16_bf16 v[0:15], v[220:223], v[224:227], v[0:15]
	s_nop 0
	s_nop 0
	s_waitcnt vmcnt(1)
	v_mfma_f32_32x32x16_bf16 v[0:15], v[228:231], v[244:247], v[0:15]
	s_nop 0
	global_load_dwordx4 v[72:75], v[18:19], off offset:2240
	s_waitcnt vmcnt(0)
	v_mfma_f32_32x32x16_bf16 v[0:15], v[248:251], v[72:75], v[0:15]
	global_load_dwordx4 v[68:71], v[76:77], off offset:224
	global_load_dwordx4 v[72:75], v[18:19], off offset:2272
	s_waitcnt vmcnt(0)
	v_mfma_f32_32x32x16_bf16 v[0:15], v[68:71], v[72:75], v[0:15]
	s_nop 11
	ds_write2st64_b32 v48, v0, v1 offset0:128 offset1:129
	ds_write2st64_b32 v48, v2, v3 offset0:130 offset1:131
	ds_write2st64_b32 v48, v4, v5 offset0:132 offset1:133
	ds_write2st64_b32 v48, v6, v7 offset0:134 offset1:135
	ds_write2st64_b32 v48, v8, v9 offset0:136 offset1:137
	ds_write2st64_b32 v48, v10, v11 offset0:138 offset1:139
	ds_write2st64_b32 v48, v12, v13 offset0:140 offset1:141
	ds_write2st64_b32 v48, v14, v15 offset0:142 offset1:143
	global_load_dwordx4 v[0:3], v[46:47], off
	global_load_dwordx4 v[4:7], v[26:27], off
	global_load_dwordx4 v[68:71], v[46:47], off offset:32
	global_load_dwordx4 v[72:75], v[28:29], off
	s_waitcnt vmcnt(2)
	v_mfma_f32_32x32x16_bf16 v[0:15], v[0:3], v[4:7], 0
	s_waitcnt vmcnt(0)
	v_mfma_f32_32x32x16_bf16 v[0:15], v[68:71], v[72:75], v[0:15]
	global_load_dwordx4 v[68:71], v[46:47], off offset:64
	global_load_dwordx4 v[72:75], v[30:31], off
	s_waitcnt vmcnt(0)
	v_mfma_f32_32x32x16_bf16 v[0:15], v[68:71], v[72:75], v[0:15]
	global_load_dwordx4 v[68:71], v[46:47], off offset:96
	global_load_dwordx4 v[72:75], v[32:33], off
	s_waitcnt vmcnt(0)
	v_mfma_f32_32x32x16_bf16 v[0:15], v[68:71], v[72:75], v[0:15]
	global_load_dwordx4 v[68:71], v[46:47], off offset:128
	global_load_dwordx4 v[72:75], v[34:35], off
	s_waitcnt vmcnt(0)
	v_mfma_f32_32x32x16_bf16 v[0:15], v[68:71], v[72:75], v[0:15]
	global_load_dwordx4 v[68:71], v[46:47], off offset:160
	global_load_dwordx4 v[72:75], v[36:37], off
	s_waitcnt vmcnt(0)
	v_mfma_f32_32x32x16_bf16 v[0:15], v[68:71], v[72:75], v[0:15]
	global_load_dwordx4 v[68:71], v[46:47], off offset:192
	global_load_dwordx4 v[72:75], v[38:39], off
	s_waitcnt vmcnt(0)
	v_mfma_f32_32x32x16_bf16 v[0:15], v[68:71], v[72:75], v[0:15]
	global_load_dwordx4 v[68:71], v[46:47], off offset:224
	global_load_dwordx4 v[72:75], v[40:41], off
	s_waitcnt vmcnt(0)
	v_mfma_f32_32x32x16_bf16 v[0:15], v[68:71], v[72:75], v[0:15]
	s_nop 11
	ds_write_b32 v49, v0
	ds_write_b32 v50, v1
	ds_write_b32 v51, v2
	ds_write_b32 v52, v3
	ds_write_b32 v53, v4
	ds_write_b32 v54, v5
	ds_write_b32 v55, v6
	ds_write_b32 v56, v7
	ds_write_b32 v57, v8
	ds_write_b32 v58, v9
	ds_write_b32 v59, v10
	ds_write_b32 v60, v11
	ds_write_b32 v61, v12
	ds_write_b32 v62, v13
	ds_write_b32 v63, v14
	ds_write_b32 v64, v15
	s_waitcnt lgkmcnt(0)
	s_barrier
; __device__ __forceinline__ float sigm(float x) { return __builtin_amdgcn_rcpf(1.0f + __expf(-x)); }
; __device__ __forceinline__ unsigned pk2(float lo, float hi) { f32x2_t v = {lo, hi}; bf16x2_t b = __builtin_convertvector(v, bf16x2_t); return __builtin_bit_cast(unsigned, b); }
; __device__ __forceinline__ float sigm(float x) { return __builtin_amdgcn_rcpf(1.0f + __expf(-x)); }
; template <int MODE, int NSEL> __device__ __forceinline__ void skinny_phase(const bf16_t* A, int lda, size_t asel, const bf16_t* Bt, size_t bsel, int K, int N, unsigned char* lds, int tid, int bx, int G, ...
;     ...
;         const int row = lane & 31, col = blk * 32 + 8 * (w >> 1) + 4 * (lane >> 5) + 2 * (w & 1);
;         float v[NSEL][2];
; #pragma unroll
;         for (int s = 0; s < NSEL; ++s)
; #pragma unroll
;             for (int e = 0; e < 2; ++e) { float t = 0.f;
; #pragma unroll
;                 for (int ww = 0; ww < 8; ++ww) t += red[((s * 8 + ww) * 16 + 2 * w + e) * 64 + lane]; v[s][e] = t; }
;         if (MODE == 1) { *(unsigned*)(Ob + (size_t)row * ldo + col) = pk2(sigm(v[0][0]), sigm(v[0][1])); }
;         else if (MODE == 2) { float o0 = 0.f, o1 = 0.f;
; #pragma unroll
;             for (int s = 0; s < NSEL; ++s) { const unsigned gwd = *(const unsigned*)(GT + (size_t)row * 6144 + s * 2048 + col); o0 += bflo(gwd) * v[s][0]; o1 += bfhi(gwd) * v[s][1]; }
;             *(unsigned*)(Ob + (size_t)(MMAIN + row) * ldo + col) = pk2(o0, o1); }
	ds_read2st64_b32 v[0:1], v43 offset1:1
	ds_read2st64_b32 v[2:3], v43 offset0:16 offset1:17
	ds_read2st64_b32 v[4:5], v43 offset0:32 offset1:33
	ds_read2st64_b32 v[6:7], v43 offset0:48 offset1:49
	ds_read2st64_b32 v[8:9], v43 offset0:64 offset1:65
	ds_read2st64_b32 v[10:11], v43 offset0:80 offset1:81
	ds_read2st64_b32 v[12:13], v43 offset0:96 offset1:97
	ds_read2st64_b32 v[14:15], v43 offset0:112 offset1:113
	ds_read2st64_b32 v[68:69], v43 offset0:128 offset1:129
	ds_read2st64_b32 v[70:71], v43 offset0:144 offset1:145
	ds_read2st64_b32 v[72:73], v43 offset0:160 offset1:161
	ds_read2st64_b32 v[74:75], v43 offset0:176 offset1:177
	ds_read2st64_b32 v[76:77], v43 offset0:192 offset1:193
	ds_read2st64_b32 v[78:79], v43 offset0:208 offset1:209
	ds_read2st64_b32 v[80:81], v43 offset0:224 offset1:225
	ds_read2st64_b32 v[82:83], v43 offset0:240 offset1:241
	ds_read2st64_b32 v[84:85], v66 offset1:16
	ds_read2st64_b32 v[86:87], v66 offset0:32 offset1:48
	ds_read2st64_b32 v[88:89], v66 offset0:64 offset1:80
	ds_read2st64_b32 v[90:91], v66 offset0:96 offset1:112
	ds_read2st64_b32 v[92:93], v67 offset1:16
	ds_read2st64_b32 v[94:95], v67 offset0:32 offset1:48
	ds_read2st64_b32 v[96:97], v67 offset0:64 offset1:80
	ds_read2st64_b32 v[98:99], v67 offset0:96 offset1:112
	v_ashrrev_i32_e32 v43, 31, v42
	s_waitcnt lgkmcnt(14)
	v_pk_add_f32 v[46:47], v[0:1], 0 op_sel_hi:[1,0]
	v_lshlrev_b64 v[0:1], 1, v[42:43]
	v_lshl_add_u64 v[100:101], v[22:23], 0, v[0:1]
	global_load_dword v43, v[100:101], off
	v_add_co_u32_e32 v100, vcc, s5, v100
	v_pk_add_f32 v[2:3], v[46:47], v[2:3]
	s_nop 0
	v_addc_co_u32_e32 v101, vcc, 0, v101, vcc
	v_pk_add_f32 v[2:3], v[2:3], v[4:5]
	v_pk_add_f32 v[4:5], v[68:69], 0 op_sel_hi:[1,0]
	v_pk_add_f32 v[2:3], v[2:3], v[6:7]
	s_waitcnt lgkmcnt(7)
	v_mov_b32_e32 v6, v84
	s_waitcnt lgkmcnt(3)
	v_mov_b32_e32 v7, v92
	v_pk_add_f32 v[4:5], v[4:5], v[70:71]
	v_pk_add_f32 v[6:7], v[6:7], 0 op_sel_hi:[1,0]
	v_mov_b32_e32 v92, v85
	v_pk_add_f32 v[2:3], v[2:3], v[8:9]
	v_pk_add_f32 v[4:5], v[4:5], v[72:73]
	v_pk_add_f32 v[6:7], v[6:7], v[92:93]
	v_mov_b32_e32 v8, v86
	s_waitcnt lgkmcnt(2)
	v_mov_b32_e32 v9, v94
	v_pk_add_f32 v[4:5], v[4:5], v[74:75]
	v_pk_add_f32 v[6:7], v[6:7], v[8:9]
	v_mov_b32_e32 v94, v87
	v_pk_add_f32 v[2:3], v[2:3], v[10:11]
	v_pk_add_f32 v[4:5], v[4:5], v[76:77]
	v_pk_add_f32 v[6:7], v[6:7], v[94:95]
	v_mov_b32_e32 v8, v88
	s_waitcnt lgkmcnt(1)
	v_mov_b32_e32 v9, v96
	v_pk_add_f32 v[2:3], v[2:3], v[12:13]
	v_pk_add_f32 v[4:5], v[4:5], v[78:79]
	v_pk_add_f32 v[6:7], v[6:7], v[8:9]
	v_mov_b32_e32 v96, v89
	v_pk_add_f32 v[2:3], v[2:3], v[14:15]
	v_pk_add_f32 v[4:5], v[4:5], v[80:81]
	v_pk_add_f32 v[6:7], v[6:7], v[96:97]
	v_mov_b32_e32 v8, v90
	s_waitcnt lgkmcnt(0)
	v_mov_b32_e32 v9, v98
	v_pk_add_f32 v[4:5], v[4:5], v[82:83]
	v_pk_add_f32 v[6:7], v[6:7], v[8:9]
	v_mov_b32_e32 v98, v91
	v_pk_add_f32 v[6:7], v[6:7], v[98:99]
	v_lshl_add_u64 v[0:1], v[24:25], 0, v[0:1]
	v_add_u32_e32 v42, 0x2000, v42
	s_waitcnt vmcnt(0)
	v_lshlrev_b32_e32 v102, 16, v43
	v_and_b32_e32 v103, 0xffff0000, v43
	global_load_dword v43, v[100:101], off offset:-4096
	v_pk_fma_f32 v[2:3], v[2:3], v[102:103], 0 op_sel_hi:[1,1,0]
	s_waitcnt vmcnt(0)
	v_lshlrev_b32_e32 v104, 16, v43
	v_and_b32_e32 v105, 0xffff0000, v43
	global_load_dword v43, v[100:101], off
	v_pk_fma_f32 v[2:3], v[4:5], v[104:105], v[2:3]
	s_waitcnt vmcnt(0)
	v_lshlrev_b32_e32 v100, 16, v43
	v_and_b32_e32 v101, 0xffff0000, v43
	v_pk_fma_f32 v[2:3], v[6:7], v[100:101], v[2:3]
	s_nop 0
	v_cvt_pk_bf16_f32 v2, v2, v3
	global_store_dword v[0:1], v2, off
	s_barrier
	s_cbranch_scc0 .LBB0_1304

; __device__ __forceinline__ float sigm(float x) { return __builtin_amdgcn_rcpf(1.0f + __expf(-x)); }
; __device__ __forceinline__ unsigned pk2(float lo, float hi) { f32x2_t v = {lo, hi}; bf16x2_t b = __builtin_convertvector(v, bf16x2_t); return __builtin_bit_cast(unsigned, b); }
; template <int MODE, int NSEL> __device__ __forceinline__ void skinny_phase(const bf16_t* A, int lda, size_t asel, const bf16_t* Bt, size_t bsel, int K, int N, unsigned char* lds, int tid, int bx, int G, ...
;     ...
;     for (int blk = G - 1 - bx; blk < (N >> 5); blk += G) {
; #pragma unroll
;         for (int s = 0; s < NSEL; ++s) {
;             const bf16_t* ap = A + s * asel + (size_t)(lane & 31) * lda + w * kw + 8 * (lane >> 5);
;             const bf16_t* bp = Bt + s * bsel + (size_t)(blk * 32 + (lane & 31)) * K + w * kw + 8 * (lane >> 5);
;             f32x16 acc;
; #pragma unroll
;             for (int i = 0; i < 16; ++i) acc[i] = 0.f;
; #pragma unroll 8
;             for (int k = 0; k < kw; k += 16) { const bf16x8 bv = *(const bf16x8*)(bp + k); const bf16x8 av = *(const bf16x8*)(ap + k); acc = __builtin_amdgcn_mfma_f32_32x32x16_bf16(bv, av, acc, 0, 0, 0); }
; #pragma unroll
;             for (int i = 0; i < 16; ++i) red[((s * 8 + w) * 16 + i) * 64 + lane] = acc[i];
;         }
;         __syncthreads();
;         const int row = lane & 31, col = blk * 32 + 8 * (w >> 1) + 4 * (lane >> 5) + 2 * (w & 1);
;         float v[NSEL][2];
; #pragma unroll
;         for (int s = 0; s < NSEL; ++s)
; #pragma unroll
;             for (int e = 0; e < 2; ++e) { float t = 0.f;
; #pragma unroll
;                 for (int ww = 0; ww < 8; ++ww) t += red[((s * 8 + ww) * 16 + 2 * w + e) * 64 + lane]; v[s][e] = t; }
;         if (MODE == 1) { *(unsigned*)(Ob + (size_t)row * ldo + col) = pk2(sigm(v[0][0]), sigm(v[0][1])); }
;         else if (MODE == 2) { float o0 = 0.f, o1 = 0.f;
; #pragma unroll
;             for (int s = 0; s < NSEL; ++s) { const unsigned gwd = *(const unsigned*)(GT + (size_t)row * 6144 + s * 2048 + col); o0 += bflo(gwd) * v[s][0]; o1 += bfhi(gwd) * v[s][1]; }
;             *(unsigned*)(Ob + (size_t)(MMAIN + row) * ldo + col) = pk2(o0, o1); }
;         else if (MODE == 3) { unsigned* hp = (unsigned*)(H + (size_t)(MMAIN + row) * DM + col); const unsigned hw = *hp; *hp = pk2(bflo(hw) + v[0][0], bfhi(hw) + v[0][1]); }
.LBB0_1382:
	global_load_dwordx4 v[76:79], v[26:27], off offset:-128
	global_load_dwordx4 v[80:83], v[28:29], off offset:-128
	global_load_dwordx4 v[84:87], v[26:27], off offset:-96
	global_load_dwordx4 v[90:93], v[28:29], off offset:-96
	global_load_dwordx4 v[94:97], v[26:27], off offset:-64
	global_load_dwordx4 v[98:101], v[28:29], off offset:-64
	global_load_dwordx4 v[102:105], v[26:27], off offset:-32
	global_load_dwordx4 v[112:115], v[28:29], off offset:-32
	global_load_dwordx4 v[116:119], v[26:27], off
	global_load_dwordx4 v[120:123], v[28:29], off
	global_load_dwordx4 v[128:131], v[26:27], off offset:32
	global_load_dwordx4 v[132:135], v[28:29], off offset:32
	global_load_dwordx4 v[136:139], v[26:27], off offset:64
	global_load_dwordx4 v[140:143], v[28:29], off offset:64
	s_nop 0
	s_addk_i32 s4, 0x80
	s_cmpk_gt_u32 s4, 0xef
	s_waitcnt vmcnt(12)
	v_mfma_f32_32x32x16_bf16 v[0:15], v[76:79], v[80:83], v[0:15]
	s_nop 0
	s_nop 0
	s_waitcnt vmcnt(10)
	v_mfma_f32_32x32x16_bf16 v[0:15], v[84:87], v[90:93], v[0:15]
	s_nop 0
	s_nop 0
	s_waitcnt vmcnt(8)
	v_mfma_f32_32x32x16_bf16 v[0:15], v[94:97], v[98:101], v[0:15]
	s_nop 0
	s_nop 0
	s_waitcnt vmcnt(6)
	v_mfma_f32_32x32x16_bf16 v[0:15], v[102:105], v[112:115], v[0:15]
	s_nop 0
	s_nop 0
	s_waitcnt vmcnt(4)
	v_mfma_f32_32x32x16_bf16 v[0:15], v[116:119], v[120:123], v[0:15]
	s_nop 0
	s_nop 0
	s_waitcnt vmcnt(2)
	v_mfma_f32_32x32x16_bf16 v[0:15], v[128:131], v[132:135], v[0:15]
	s_nop 0
	s_nop 0
	s_waitcnt vmcnt(0)
	v_mfma_f32_32x32x16_bf16 v[0:15], v[136:139], v[140:143], v[0:15]
	global_load_dwordx4 v[32:35], v[26:27], off offset:96
	global_load_dwordx4 v[36:39], v[28:29], off offset:96
	v_lshl_add_u64 v[28:29], v[28:29], 0, s[64:65]
	v_lshl_add_u64 v[26:27], v[26:27], 0, s[64:65]
	s_waitcnt vmcnt(0)
	v_mfma_f32_32x32x16_bf16 v[0:15], v[32:35], v[36:39], v[0:15]
	s_cbranch_scc0 .LBB0_1382
	s_nop 10
	ds_write2st64_b32 v30, v0, v1 offset1:1
	ds_write2st64_b32 v30, v2, v3 offset0:2 offset1:3
	ds_write2st64_b32 v30, v4, v5 offset0:4 offset1:5
	ds_write2st64_b32 v30, v6, v7 offset0:6 offset1:7
	ds_write2st64_b32 v30, v8, v9 offset0:8 offset1:9
	ds_write2st64_b32 v30, v10, v11 offset0:10 offset1:11
	ds_write2st64_b32 v30, v12, v13 offset0:12 offset1:13
	ds_write2st64_b32 v30, v14, v15 offset0:14 offset1:15
	v_lshl_add_u32 v0, s3, 5, v17
	v_ashrrev_i32_e32 v1, 31, v0
	v_lshl_add_u64 v[0:1], v[0:1], 1, v[18:19]
	s_waitcnt lgkmcnt(0)
	s_barrier
	global_load_dword v25, v[0:1], off
	ds_read2st64_b32 v[2:3], v31 offset1:1
	ds_read2st64_b32 v[4:5], v31 offset0:16 offset1:17
	ds_read2st64_b32 v[6:7], v31 offset0:32 offset1:33
	ds_read2st64_b32 v[8:9], v31 offset0:48 offset1:49
	ds_read2st64_b32 v[10:11], v31 offset0:64 offset1:65
	ds_read2st64_b32 v[12:13], v31 offset0:80 offset1:81
	ds_read2st64_b32 v[14:15], v31 offset0:96 offset1:97
	ds_read2st64_b32 v[26:27], v31 offset0:112 offset1:113
	s_waitcnt lgkmcnt(7)
	v_pk_add_f32 v[2:3], v[2:3], 0 op_sel_hi:[1,0]
	s_add_i32 s4, s3, 0x100
	s_waitcnt lgkmcnt(6)
	v_pk_add_f32 v[2:3], v[2:3], v[4:5]
	v_add_u32_e32 v24, 0x2000, v24
	s_waitcnt lgkmcnt(5)
	v_pk_add_f32 v[2:3], v[2:3], v[6:7]
	s_cmpk_gt_i32 s3, 0xff3f
	s_waitcnt lgkmcnt(4)
	v_pk_add_f32 v[2:3], v[2:3], v[8:9]
	s_mov_b32 s3, s4
	s_waitcnt lgkmcnt(3)
	v_pk_add_f32 v[2:3], v[2:3], v[10:11]
	s_waitcnt vmcnt(0)
	v_lshlrev_b32_e32 v4, 16, v25
	s_waitcnt lgkmcnt(2)
	v_pk_add_f32 v[2:3], v[2:3], v[12:13]
	v_and_b32_e32 v5, 0xffff0000, v25
	s_waitcnt lgkmcnt(1)
	v_pk_add_f32 v[2:3], v[2:3], v[14:15]
	s_waitcnt lgkmcnt(0)
	v_pk_add_f32 v[2:3], v[2:3], v[26:27]
	s_nop 0
	v_pk_add_f32 v[2:3], v[2:3], v[4:5]
	s_nop 0
	v_cvt_pk_bf16_f32 v2, v2, v3
	global_store_dword v[0:1], v2, off
	s_barrier
	s_cbranch_scc0 .LBB0_1381

; __device__ __forceinline__ float sigm(float x) { return __builtin_amdgcn_rcpf(1.0f + __expf(-x)); }
; __device__ __forceinline__ float sigm(float x) { return __builtin_amdgcn_rcpf(1.0f + __expf(-x)); }
; template <int MODE, int NSEL> __device__ __forceinline__ void skinny_phase(const bf16_t* A, int lda, size_t asel, const bf16_t* Bt, size_t bsel, int K, int N, unsigned char* lds, int tid, int bx, int G, ...
;     ...
;     for (int blk = G - 1 - bx; blk < (N >> 5); blk += G) {
; #pragma unroll
;         for (int s = 0; s < NSEL; ++s) {
;             const bf16_t* ap = A + s * asel + (size_t)(lane & 31) * lda + w * kw + 8 * (lane >> 5);
;             const bf16_t* bp = Bt + s * bsel + (size_t)(blk * 32 + (lane & 31)) * K + w * kw + 8 * (lane >> 5);
;             f32x16 acc;
; #pragma unroll
;             for (int i = 0; i < 16; ++i) acc[i] = 0.f;
; #pragma unroll 8
;             for (int k = 0; k < kw; k += 16) { const bf16x8 bv = *(const bf16x8*)(bp + k); const bf16x8 av = *(const bf16x8*)(ap + k); acc = __builtin_amdgcn_mfma_f32_32x32x16_bf16(bv, av, acc, 0, 0, 0); }
; #pragma unroll
;             for (int i = 0; i < 16; ++i) red[((s * 8 + w) * 16 + i) * 64 + lane] = acc[i];
;         }
;         __syncthreads();
;         const int row = lane & 31, col = blk * 32 + 8 * (w >> 1) + 4 * (lane >> 5) + 2 * (w & 1);
;         float v[NSEL][2];
; #pragma unroll
;         for (int s = 0; s < NSEL; ++s)
; #pragma unroll
;             for (int e = 0; e < 2; ++e) { float t = 0.f;
; #pragma unroll
;                 for (int ww = 0; ww < 8; ++ww) t += red[((s * 8 + ww) * 16 + 2 * w + e) * 64 + lane]; v[s][e] = t; }
;         if (MODE == 1) { *(unsigned*)(Ob + (size_t)row * ldo + col) = pk2(sigm(v[0][0]), sigm(v[0][1])); }
;         else if (MODE == 2) { float o0 = 0.f, o1 = 0.f;
; #pragma unroll
;             for (int s = 0; s < NSEL; ++s) { const unsigned gwd = *(const unsigned*)(GT + (size_t)row * 6144 + s * 2048 + col); o0 += bflo(gwd) * v[s][0]; o1 += bfhi(gwd) * v[s][1]; }
;             *(unsigned*)(Ob + (size_t)(MMAIN + row) * ldo + col) = pk2(o0, o1); }
;         else if (MODE == 3) { unsigned* hp = (unsigned*)(H + (size_t)(MMAIN + row) * DM + col); const unsigned hw = *hp; *hp = pk2(bflo(hw) + v[0][0], bfhi(hw) + v[0][1]); }
;         else { *(unsigned*)(Ob + (size_t)(16384 + row) * ldo + col) = pk2(v[0][0], v[0][1]); }
.LBB0_1517:
	global_load_dwordx4 v[76:79], v[26:27], off offset:-128
	global_load_dwordx4 v[80:83], v[28:29], off offset:-128
	global_load_dwordx4 v[84:87], v[26:27], off offset:-96
	global_load_dwordx4 v[90:93], v[28:29], off offset:-96
	global_load_dwordx4 v[94:97], v[26:27], off offset:-64
	global_load_dwordx4 v[98:101], v[28:29], off offset:-64
	global_load_dwordx4 v[102:105], v[26:27], off offset:-32
	global_load_dwordx4 v[112:115], v[28:29], off offset:-32
	global_load_dwordx4 v[116:119], v[26:27], off
	global_load_dwordx4 v[120:123], v[28:29], off
	global_load_dwordx4 v[128:131], v[26:27], off offset:32
	global_load_dwordx4 v[132:135], v[28:29], off offset:32
	global_load_dwordx4 v[136:139], v[26:27], off offset:64
	global_load_dwordx4 v[140:143], v[28:29], off offset:64
	s_nop 0
	s_addk_i32 s4, 0x80
	s_cmpk_gt_u32 s4, 0xef
	s_waitcnt vmcnt(12)
	v_mfma_f32_32x32x16_bf16 v[0:15], v[76:79], v[80:83], v[0:15]
	s_nop 0
	s_nop 0
	s_waitcnt vmcnt(10)
	v_mfma_f32_32x32x16_bf16 v[0:15], v[84:87], v[90:93], v[0:15]
	s_nop 0
	s_nop 0
	s_waitcnt vmcnt(8)
	v_mfma_f32_32x32x16_bf16 v[0:15], v[94:97], v[98:101], v[0:15]
	s_nop 0
	s_nop 0
	s_waitcnt vmcnt(6)
	v_mfma_f32_32x32x16_bf16 v[0:15], v[102:105], v[112:115], v[0:15]
	s_nop 0
	s_nop 0
	s_waitcnt vmcnt(4)
	v_mfma_f32_32x32x16_bf16 v[0:15], v[116:119], v[120:123], v[0:15]
	s_nop 0
	s_nop 0
	s_waitcnt vmcnt(2)
	v_mfma_f32_32x32x16_bf16 v[0:15], v[128:131], v[132:135], v[0:15]
	s_nop 0
	s_nop 0
	s_waitcnt vmcnt(0)
	v_mfma_f32_32x32x16_bf16 v[0:15], v[136:139], v[140:143], v[0:15]
	global_load_dwordx4 v[32:35], v[26:27], off offset:96
	global_load_dwordx4 v[36:39], v[28:29], off offset:96
	v_lshl_add_u64 v[28:29], v[28:29], 0, s[64:65]
	v_lshl_add_u64 v[26:27], v[26:27], 0, s[64:65]
	s_waitcnt vmcnt(0)
	v_mfma_f32_32x32x16_bf16 v[0:15], v[32:35], v[36:39], v[0:15]
	s_cbranch_scc0 .LBB0_1517
	s_nop 10
	ds_write2st64_b32 v30, v0, v1 offset1:1
	ds_write2st64_b32 v30, v2, v3 offset0:2 offset1:3
	ds_write2st64_b32 v30, v4, v5 offset0:4 offset1:5
	ds_write2st64_b32 v30, v6, v7 offset0:6 offset1:7
	ds_write2st64_b32 v30, v8, v9 offset0:8 offset1:9
	ds_write2st64_b32 v30, v10, v11 offset0:10 offset1:11
	ds_write2st64_b32 v30, v12, v13 offset0:12 offset1:13
	ds_write2st64_b32 v30, v14, v15 offset0:14 offset1:15
	s_waitcnt lgkmcnt(0)
	s_barrier
	ds_read2st64_b32 v[0:1], v31 offset1:1
	ds_read2st64_b32 v[2:3], v31 offset0:16 offset1:17
	ds_read2st64_b32 v[4:5], v31 offset0:32 offset1:33
	ds_read2st64_b32 v[6:7], v31 offset0:48 offset1:49
	ds_read2st64_b32 v[8:9], v31 offset0:64 offset1:65
	ds_read2st64_b32 v[10:11], v31 offset0:80 offset1:81
	ds_read2st64_b32 v[12:13], v31 offset0:96 offset1:97
	ds_read2st64_b32 v[14:15], v31 offset0:112 offset1:113
	s_waitcnt lgkmcnt(7)
	v_pk_add_f32 v[0:1], v[0:1], 0 op_sel_hi:[1,0]
	s_add_i32 s4, s3, 0x100
	s_waitcnt lgkmcnt(6)
	v_pk_add_f32 v[0:1], v[0:1], v[2:3]
	v_lshl_add_u32 v2, s3, 5, v17
	s_waitcnt lgkmcnt(5)
	v_pk_add_f32 v[0:1], v[0:1], v[4:5]
	v_ashrrev_i32_e32 v3, 31, v2
	s_waitcnt lgkmcnt(4)
	v_pk_add_f32 v[0:1], v[0:1], v[6:7]
	v_add_u32_e32 v24, 0x2000, v24
	s_waitcnt lgkmcnt(3)
	v_pk_add_f32 v[0:1], v[0:1], v[8:9]
	s_cmpk_gt_i32 s3, 0x5f
	s_waitcnt lgkmcnt(2)
	v_pk_add_f32 v[0:1], v[0:1], v[10:11]
	s_mov_b32 s3, s4
	s_waitcnt lgkmcnt(1)
	v_pk_add_f32 v[0:1], v[0:1], v[12:13]
	s_waitcnt lgkmcnt(0)
	v_pk_add_f32 v[0:1], v[0:1], v[14:15]
	s_nop 0
	v_cvt_pk_bf16_f32 v4, v0, v1
	v_lshl_add_u64 v[0:1], v[2:3], 1, v[18:19]
	global_store_dword v[0:1], v4, off
	s_barrier
	s_cbranch_scc0 .LBB0_1516

; template <int MODE, int NSEL> __device__ __forceinline__ void skinny_phase(const bf16_t* A, int lda, size_t asel, const bf16_t* Bt, size_t bsel, int K, int N, unsigned char* lds, int tid, int bx, int G, ...
;     ...
;     for (int blk = G - 1 - bx; blk < (N >> 5); blk += G) {
; #pragma unroll
;         for (int s = 0; s < NSEL; ++s) {
;             const bf16_t* ap = A + s * asel + (size_t)(lane & 31) * lda + w * kw + 8 * (lane >> 5);
;             const bf16_t* bp = Bt + s * bsel + (size_t)(blk * 32 + (lane & 31)) * K + w * kw + 8 * (lane >> 5);
;             f32x16 acc;
; #pragma unroll
;             for (int i = 0; i < 16; ++i) acc[i] = 0.f;
; #pragma unroll 8
;             for (int k = 0; k < kw; k += 16) { const bf16x8 bv = *(const bf16x8*)(bp + k); const bf16x8 av = *(const bf16x8*)(ap + k); acc = __builtin_amdgcn_mfma_f32_32x32x16_bf16(bv, av, acc, 0, 0, 0); }
; #pragma unroll
;             for (int i = 0; i < 16; ++i) red[((s * 8 + w) * 16 + i) * 64 + lane] = acc[i];
.LBB0_1661:
	v_mad_i64_i32 v[26:27], s[4:5], v17, s27, v[20:21]
	global_load_dwordx4 v[76:79], v[26:27], off
	global_load_dwordx4 v[80:83], v[18:19], off
	global_load_dwordx4 v[84:87], v[26:27], off offset:32
	global_load_dwordx4 v[90:93], v[18:19], off offset:32
	global_load_dwordx4 v[94:97], v[26:27], off offset:64
	global_load_dwordx4 v[98:101], v[18:19], off offset:64
	global_load_dwordx4 v[102:105], v[26:27], off offset:96
	global_load_dwordx4 v[112:115], v[18:19], off offset:96
	global_load_dwordx4 v[116:119], v[26:27], off offset:128
	global_load_dwordx4 v[120:123], v[18:19], off offset:128
	global_load_dwordx4 v[128:131], v[26:27], off offset:160
	global_load_dwordx4 v[132:135], v[18:19], off offset:160
	global_load_dwordx4 v[136:139], v[26:27], off offset:192
	global_load_dwordx4 v[140:143], v[18:19], off offset:192
	global_load_dwordx4 v[144:147], v[26:27], off offset:224
	global_load_dwordx4 v[148:151], v[18:19], off offset:224
	global_load_dwordx4 v[152:155], v[26:27], off offset:256
	global_load_dwordx4 v[156:159], v[18:19], off offset:256
	global_load_dwordx4 v[160:163], v[26:27], off offset:288
	global_load_dwordx4 v[164:167], v[18:19], off offset:288
	global_load_dwordx4 v[168:171], v[26:27], off offset:320
	global_load_dwordx4 v[172:175], v[18:19], off offset:320
	global_load_dwordx4 v[176:179], v[26:27], off offset:352
	global_load_dwordx4 v[180:183], v[18:19], off offset:352
	global_load_dwordx4 v[184:187], v[26:27], off offset:384
	global_load_dwordx4 v[188:191], v[18:19], off offset:384
	global_load_dwordx4 v[196:199], v[26:27], off offset:416
	global_load_dwordx4 v[200:203], v[18:19], off offset:416
	global_load_dwordx4 v[204:207], v[26:27], off offset:448
	global_load_dwordx4 v[208:211], v[18:19], off offset:448
	s_nop 0
	s_nop 0
	s_nop 0
	v_ashrrev_i32_e32 v25, 31, v24
	s_addk_i32 s3, 0x100
	v_add_u32_e32 v17, 0x2000, v17
	s_cmpk_lt_i32 s3, 0xff40
	s_waitcnt vmcnt(28)
	v_mfma_f32_32x32x16_bf16 v[0:15], v[76:79], v[80:83], 0
	s_waitcnt vmcnt(26)
	v_mfma_f32_32x32x16_bf16 v[0:15], v[84:87], v[90:93], v[0:15]
	s_nop 0
	s_nop 0
	s_waitcnt vmcnt(24)
	v_mfma_f32_32x32x16_bf16 v[0:15], v[94:97], v[98:101], v[0:15]
	s_nop 0
	s_nop 0
	s_waitcnt vmcnt(22)
	v_mfma_f32_32x32x16_bf16 v[0:15], v[102:105], v[112:115], v[0:15]
	s_nop 0
	s_nop 0
	s_waitcnt vmcnt(20)
	v_mfma_f32_32x32x16_bf16 v[0:15], v[116:119], v[120:123], v[0:15]
	s_nop 0
	s_nop 0
	s_waitcnt vmcnt(18)
	v_mfma_f32_32x32x16_bf16 v[0:15], v[128:131], v[132:135], v[0:15]
	s_nop 0
	s_nop 0
	s_waitcnt vmcnt(16)
	v_mfma_f32_32x32x16_bf16 v[0:15], v[136:139], v[140:143], v[0:15]
	s_nop 0
	s_nop 0
	s_waitcnt vmcnt(14)
	v_mfma_f32_32x32x16_bf16 v[0:15], v[144:147], v[148:151], v[0:15]
	s_nop 0
	s_nop 0
	s_waitcnt vmcnt(12)
	v_mfma_f32_32x32x16_bf16 v[0:15], v[152:155], v[156:159], v[0:15]
	s_nop 0
	s_nop 0
	s_waitcnt vmcnt(10)
	v_mfma_f32_32x32x16_bf16 v[0:15], v[160:163], v[164:167], v[0:15]
	s_nop 0
	s_nop 0
	s_waitcnt vmcnt(8)
	v_mfma_f32_32x32x16_bf16 v[0:15], v[168:171], v[172:175], v[0:15]
	s_nop 0
	s_nop 0
	s_waitcnt vmcnt(6)
	v_mfma_f32_32x32x16_bf16 v[0:15], v[176:179], v[180:183], v[0:15]
	s_nop 0
	s_nop 0
	s_waitcnt vmcnt(4)
	v_mfma_f32_32x32x16_bf16 v[0:15], v[184:187], v[188:191], v[0:15]
	s_nop 0
	s_nop 0
	s_waitcnt vmcnt(2)
	v_mfma_f32_32x32x16_bf16 v[0:15], v[196:199], v[200:203], v[0:15]
	s_nop 0
	s_nop 0
	s_waitcnt vmcnt(0)
	v_mfma_f32_32x32x16_bf16 v[0:15], v[204:207], v[208:211], v[0:15]
	global_load_dwordx4 v[76:79], v[26:27], off offset:480
	global_load_dwordx4 v[80:83], v[18:19], off offset:480
	global_load_dwordx4 v[84:87], v[26:27], off offset:512
	global_load_dwordx4 v[90:93], v[18:19], off offset:512
	global_load_dwordx4 v[94:97], v[26:27], off offset:544
	global_load_dwordx4 v[98:101], v[18:19], off offset:544
	global_load_dwordx4 v[102:105], v[26:27], off offset:576
	global_load_dwordx4 v[112:115], v[18:19], off offset:576
	global_load_dwordx4 v[116:119], v[26:27], off offset:608
	global_load_dwordx4 v[120:123], v[18:19], off offset:608
	global_load_dwordx4 v[128:131], v[26:27], off offset:640
	global_load_dwordx4 v[132:135], v[18:19], off offset:640
	global_load_dwordx4 v[136:139], v[26:27], off offset:672
	global_load_dwordx4 v[140:143], v[18:19], off offset:672
	global_load_dwordx4 v[144:147], v[26:27], off offset:704
	global_load_dwordx4 v[148:151], v[18:19], off offset:704
	global_load_dwordx4 v[152:155], v[26:27], off offset:736
	global_load_dwordx4 v[156:159], v[18:19], off offset:736
	global_load_dwordx4 v[160:163], v[26:27], off offset:768
	global_load_dwordx4 v[164:167], v[18:19], off offset:768
	global_load_dwordx4 v[168:171], v[26:27], off offset:800
	global_load_dwordx4 v[172:175], v[18:19], off offset:800
	global_load_dwordx4 v[176:179], v[26:27], off offset:832
	global_load_dwordx4 v[180:183], v[18:19], off offset:832
	global_load_dwordx4 v[184:187], v[26:27], off offset:864
	global_load_dwordx4 v[188:191], v[18:19], off offset:864
	global_load_dwordx4 v[196:199], v[26:27], off offset:896
	global_load_dwordx4 v[200:203], v[18:19], off offset:896
	global_load_dwordx4 v[204:207], v[26:27], off offset:928
	global_load_dwordx4 v[208:211], v[18:19], off offset:928
	s_nop 0
	s_waitcnt vmcnt(28)
	v_mfma_f32_32x32x16_bf16 v[0:15], v[76:79], v[80:83], v[0:15]
	s_nop 0
	s_nop 0
	s_waitcnt vmcnt(26)
	v_mfma_f32_32x32x16_bf16 v[0:15], v[84:87], v[90:93], v[0:15]
	s_nop 0
	s_nop 0
	s_waitcnt vmcnt(24)
	v_mfma_f32_32x32x16_bf16 v[0:15], v[94:97], v[98:101], v[0:15]
	s_nop 0
	s_nop 0
	s_waitcnt vmcnt(22)
	v_mfma_f32_32x32x16_bf16 v[0:15], v[102:105], v[112:115], v[0:15]
	s_nop 0
	s_nop 0
	s_waitcnt vmcnt(20)
; __device__ __forceinline__ float sigm(float x) { return __builtin_amdgcn_rcpf(1.0f + __expf(-x)); }
; __device__ __forceinline__ float sigm(float x) { return __builtin_amdgcn_rcpf(1.0f + __expf(-x)); }
; template <int MODE, int NSEL> __device__ __forceinline__ void skinny_phase(const bf16_t* A, int lda, size_t asel, const bf16_t* Bt, size_t bsel, int K, int N, unsigned char* lds, int tid, int bx, int G, ...
;     ...
;             for (int i = 0; i < 16; ++i) red[((s * 8 + w) * 16 + i) * 64 + lane] = acc[i];
;         }
;         __syncthreads();
;         const int row = lane & 31, col = blk * 32 + 8 * (w >> 1) + 4 * (lane >> 5) + 2 * (w & 1);
;         float v[NSEL][2];
; #pragma unroll
;         for (int s = 0; s < NSEL; ++s)
; #pragma unroll
;             for (int e = 0; e < 2; ++e) { float t = 0.f;
; #pragma unroll
;                 for (int ww = 0; ww < 8; ++ww) t += red[((s * 8 + ww) * 16 + 2 * w + e) * 64 + lane]; v[s][e] = t; }
;         if (MODE == 1) { *(unsigned*)(Ob + (size_t)row * ldo + col) = pk2(sigm(v[0][0]), sigm(v[0][1])); }
;         else if (MODE == 2) { float o0 = 0.f, o1 = 0.f;
; #pragma unroll
;             for (int s = 0; s < NSEL; ++s) { const unsigned gwd = *(const unsigned*)(GT + (size_t)row * 6144 + s * 2048 + col); o0 += bflo(gwd) * v[s][0]; o1 += bfhi(gwd) * v[s][1]; }
;             *(unsigned*)(Ob + (size_t)(MMAIN + row) * ldo + col) = pk2(o0, o1); }
;         else if (MODE == 3) { unsigned* hp = (unsigned*)(H + (size_t)(MMAIN + row) * DM + col); const unsigned hw = *hp; *hp = pk2(bflo(hw) + v[0][0], bfhi(hw) + v[0][1]); }
; __global__ void __launch_bounds__(512, 2) fwd_megakernel(Ptrs Parg) {
;     ...
;             GSYNC();
;             for (int rep = 0; rep < REP_MEM; ++rep) if (PH(15)) { TIDS; ffn_act_phase(P, l, half, gw, NGW, lane); }
;             GSYNC();
;             if (PH(16)) { PHP; bf16_t* G2 = (bf16_t*)(P.ws + WS_R + (size_t)16640 * 11264 * 2); pg8::Gemm g{G2, WdT, DFF, DFF, 1, 0, 0}; pg8::Sched S{64, 8, 1, G, bx, 64 * half, 64};
;               pg8::EpiResid E{H};
;               pg8::gemm_phase<pg8::EpiResid, pg8::Sched, GEMM_ALIGN, GEMM_SP2>(glds, g, S, E); }
;             if (half == 1) { TIDS; skinny_phase<3, 1>((const bf16_t*)(P.ws + WS_R + (size_t)16640 * 11264 * 2) + (size_t)16384 * DFF, DFF, 0, WdT, 0, DFF, DM, lds, tid, bx, G, nullptr, nullptr, 0, H); }
;             GSYNC();
	v_mfma_f32_32x32x16_bf16 v[0:15], v[116:119], v[120:123], v[0:15]
	s_nop 0
	s_nop 0
	s_waitcnt vmcnt(18)
	v_mfma_f32_32x32x16_bf16 v[0:15], v[128:131], v[132:135], v[0:15]
	s_nop 0
	s_nop 0
	s_waitcnt vmcnt(16)
	v_mfma_f32_32x32x16_bf16 v[0:15], v[136:139], v[140:143], v[0:15]
	s_nop 0
	s_nop 0
	s_waitcnt vmcnt(14)
	v_mfma_f32_32x32x16_bf16 v[0:15], v[144:147], v[148:151], v[0:15]
	s_nop 0
	s_nop 0
	s_waitcnt vmcnt(12)
	v_mfma_f32_32x32x16_bf16 v[0:15], v[152:155], v[156:159], v[0:15]
	s_nop 0
	s_nop 0
	s_waitcnt vmcnt(10)
	v_mfma_f32_32x32x16_bf16 v[0:15], v[160:163], v[164:167], v[0:15]
	s_nop 0
	s_nop 0
	s_waitcnt vmcnt(8)
	v_mfma_f32_32x32x16_bf16 v[0:15], v[168:171], v[172:175], v[0:15]
	s_nop 0
	s_nop 0
	s_waitcnt vmcnt(6)
	v_mfma_f32_32x32x16_bf16 v[0:15], v[176:179], v[180:183], v[0:15]
	s_nop 0
	s_nop 0
	s_waitcnt vmcnt(4)
	v_mfma_f32_32x32x16_bf16 v[0:15], v[184:187], v[188:191], v[0:15]
	s_nop 0
	s_nop 0
	s_waitcnt vmcnt(2)
	v_mfma_f32_32x32x16_bf16 v[0:15], v[196:199], v[200:203], v[0:15]
	s_nop 0
	s_nop 0
	s_waitcnt vmcnt(0)
	v_mfma_f32_32x32x16_bf16 v[0:15], v[204:207], v[208:211], v[0:15]
	global_load_dwordx4 v[76:79], v[26:27], off offset:960
	global_load_dwordx4 v[80:83], v[18:19], off offset:960
	global_load_dwordx4 v[84:87], v[26:27], off offset:992
	global_load_dwordx4 v[90:93], v[18:19], off offset:992
	global_load_dwordx4 v[94:97], v[26:27], off offset:1024
	global_load_dwordx4 v[98:101], v[18:19], off offset:1024
	global_load_dwordx4 v[102:105], v[26:27], off offset:1056
	global_load_dwordx4 v[112:115], v[18:19], off offset:1056
	global_load_dwordx4 v[116:119], v[26:27], off offset:1088
	global_load_dwordx4 v[120:123], v[18:19], off offset:1088
	global_load_dwordx4 v[128:131], v[26:27], off offset:1120
	global_load_dwordx4 v[132:135], v[18:19], off offset:1120
	global_load_dwordx4 v[136:139], v[26:27], off offset:1152
	global_load_dwordx4 v[140:143], v[18:19], off offset:1152
	global_load_dwordx4 v[144:147], v[26:27], off offset:1184
	global_load_dwordx4 v[148:151], v[18:19], off offset:1184
	global_load_dwordx4 v[152:155], v[26:27], off offset:1216
	global_load_dwordx4 v[156:159], v[18:19], off offset:1216
	global_load_dwordx4 v[160:163], v[26:27], off offset:1248
	global_load_dwordx4 v[164:167], v[18:19], off offset:1248
	global_load_dwordx4 v[168:171], v[26:27], off offset:1280
	global_load_dwordx4 v[172:175], v[18:19], off offset:1280
	global_load_dwordx4 v[176:179], v[26:27], off offset:1312
	global_load_dwordx4 v[180:183], v[18:19], off offset:1312
	global_load_dwordx4 v[184:187], v[26:27], off offset:1344
	global_load_dwordx4 v[188:191], v[18:19], off offset:1344
	global_load_dwordx4 v[196:199], v[26:27], off offset:1376
	s_nop 0
	s_waitcnt vmcnt(25)
	v_mfma_f32_32x32x16_bf16 v[0:15], v[76:79], v[80:83], v[0:15]
	s_nop 0
	s_nop 0
	s_waitcnt vmcnt(23)
	v_mfma_f32_32x32x16_bf16 v[0:15], v[84:87], v[90:93], v[0:15]
	s_nop 0
	s_nop 0
	s_waitcnt vmcnt(21)
	v_mfma_f32_32x32x16_bf16 v[0:15], v[94:97], v[98:101], v[0:15]
	s_nop 0
	s_nop 0
	s_waitcnt vmcnt(19)
	v_mfma_f32_32x32x16_bf16 v[0:15], v[102:105], v[112:115], v[0:15]
	s_nop 0
	s_nop 0
	s_waitcnt vmcnt(17)
	v_mfma_f32_32x32x16_bf16 v[0:15], v[116:119], v[120:123], v[0:15]
	s_nop 0
	s_nop 0
	s_waitcnt vmcnt(15)
	v_mfma_f32_32x32x16_bf16 v[0:15], v[128:131], v[132:135], v[0:15]
	s_nop 0
	s_nop 0
	s_waitcnt vmcnt(13)
	v_mfma_f32_32x32x16_bf16 v[0:15], v[136:139], v[140:143], v[0:15]
	s_nop 0
	s_nop 0
	s_waitcnt vmcnt(11)
	v_mfma_f32_32x32x16_bf16 v[0:15], v[144:147], v[148:151], v[0:15]
	s_nop 0
	s_nop 0
	s_waitcnt vmcnt(9)
	v_mfma_f32_32x32x16_bf16 v[0:15], v[152:155], v[156:159], v[0:15]
	s_nop 0
	s_nop 0
	s_waitcnt vmcnt(7)
	v_mfma_f32_32x32x16_bf16 v[0:15], v[160:163], v[164:167], v[0:15]
	s_nop 0
	s_nop 0
	s_waitcnt vmcnt(5)
	v_mfma_f32_32x32x16_bf16 v[0:15], v[168:171], v[172:175], v[0:15]
	s_nop 0
	s_nop 0
	s_waitcnt vmcnt(3)
	v_mfma_f32_32x32x16_bf16 v[0:15], v[176:179], v[180:183], v[0:15]
	s_nop 0
	s_nop 0
	s_waitcnt vmcnt(1)
	v_mfma_f32_32x32x16_bf16 v[0:15], v[184:187], v[188:191], v[0:15]
	s_nop 0
	global_load_dwordx4 v[34:37], v[18:19], off offset:1376
	v_lshl_add_u64 v[26:27], v[24:25], 1, v[22:23]
	v_add_u32_e32 v24, 0x2000, v24
	s_waitcnt vmcnt(0)
	v_mfma_f32_32x32x16_bf16 v[0:15], v[196:199], v[34:37], v[0:15]
	s_nop 11
	ds_write2st64_b32 v28, v0, v1 offset1:1
	ds_write2st64_b32 v28, v2, v3 offset0:2 offset1:3
	ds_write2st64_b32 v28, v4, v5 offset0:4 offset1:5
	ds_write2st64_b32 v28, v6, v7 offset0:6 offset1:7
	ds_write2st64_b32 v28, v8, v9 offset0:8 offset1:9
	ds_write2st64_b32 v28, v10, v11 offset0:10 offset1:11
	ds_write2st64_b32 v28, v12, v13 offset0:12 offset1:13
	ds_write2st64_b32 v28, v14, v15 offset0:14 offset1:15
	s_waitcnt lgkmcnt(0)
	s_barrier
	ds_read2st64_b32 v[0:1], v29 offset1:1
	ds_read2st64_b32 v[2:3], v29 offset0:16 offset1:17
	ds_read2st64_b32 v[4:5], v29 offset0:32 offset1:33
	ds_read2st64_b32 v[6:7], v29 offset0:48 offset1:49
	ds_read2st64_b32 v[8:9], v29 offset0:64 offset1:65
	ds_read2st64_b32 v[10:11], v29 offset0:80 offset1:81
	ds_read2st64_b32 v[12:13], v29 offset0:96 offset1:97
	ds_read2st64_b32 v[14:15], v29 offset0:112 offset1:113
	global_load_dword v25, v[26:27], off
	s_waitcnt lgkmcnt(7)
	v_pk_add_f32 v[0:1], v[0:1], 0 op_sel_hi:[1,0]
	s_waitcnt vmcnt(0)
	v_lshlrev_b32_e32 v30, 16, v25
	s_waitcnt lgkmcnt(6)
	v_pk_add_f32 v[0:1], v[0:1], v[2:3]
	v_and_b32_e32 v31, 0xffff0000, v25
	s_waitcnt lgkmcnt(5)
	v_pk_add_f32 v[0:1], v[0:1], v[4:5]
	s_waitcnt lgkmcnt(4)
	v_pk_add_f32 v[0:1], v[0:1], v[6:7]
	s_waitcnt lgkmcnt(3)
	v_pk_add_f32 v[0:1], v[0:1], v[8:9]
	s_waitcnt lgkmcnt(2)
	v_pk_add_f32 v[0:1], v[0:1], v[10:11]
	s_waitcnt lgkmcnt(1)
	v_pk_add_f32 v[0:1], v[0:1], v[12:13]
	s_waitcnt lgkmcnt(0)
	v_pk_add_f32 v[0:1], v[0:1], v[14:15]
	s_nop 0
	v_pk_add_f32 v[0:1], v[0:1], v[30:31]
	s_nop 0
	v_cvt_pk_bf16_f32 v0, v0, v1
	global_store_dword v[26:27], v0, off
	s_barrier
	s_cbranch_scc1 .LBB0_1661
.LBB0_1662:
	s_waitcnt vmcnt(0)
	s_barrier
	s_getreg_b32 s3, hwreg(HW_REG_HW_ID, 0, 6)
	s_and_b32 s3, s3, 63
	s_lshl_b32 s3, s3, 2
	s_add_i32 s3, s3, 0
	s_add_i32 s3, s3, 0x27ef0
	v_mov_b32_e32 v0, s3
	ds_read_b32 v0, v0
	s_waitcnt lgkmcnt(0)
	v_readfirstlane_b32 s3, v0
	s_nop 1
	v_lshl_add_u32 v0, s3, 6, v213
	s_nop 0
	v_cmp_eq_u32_e32 vcc, 0, v0
	s_and_saveexec_b64 s[4:5], vcc
	s_cbranch_execz .LBB0_1496
	s_andn2_b64 vcc, exec, s[40:41]
	s_cbranch_vccnz .LBB0_1496
	v_mov_b32_e32 v0, s78
	s_waitcnt vmcnt(0) expcnt(0) lgkmcnt(0)
	ds_read_b32 v2, v0
	v_mov_b32_e32 v0, s79
	ds_read_b32 v0, v0
	s_waitcnt lgkmcnt(1)
	v_cmp_ne_u32_e32 vcc, 0, v2
	s_cbranch_vccnz .LBB0_1678
	s_mov_b32 s3, 1
	s_branch .LBB0_1666
